# wave-priority steering: s_setprio 1/0 around the four MFMA clusters of the differential-attention loop, as the baseline already does in the MLA and NA loops
# baseline (speedup 1.0000x reference)
; DI f32x16 mfma32(bf16x8 a, bf16x8 b, f32x16 c) { return __builtin_amdgcn_mfma_f32_32x32x16_bf16(a, b, c, 0, 0, 0); }
; DI void attn_diff_unit(const Params& p, int li, int b, int h, int qb, char* smem, bool pre, int nh, bool has_next) {
;     ...
;       const int kbase = kt * 128 + sub * 64;
;       const int relmin = kbase - (qb * 128 + 127), relmax = kbase + 63 - qb * 128;
;       const float cb = (relmin >= 128) ? cR : ((relmax <= -128) ? cL : 0.f);
;       f32x16 s0, s1;
; #pragma unroll
;       for (int i = 0; i < 16; ++i) { s0[i] = cb - m; s1[i] = cb - m; }
;       {
;         bf16x8 kf[8];
; #pragma unroll
;         for (int s = 0; s < 4; ++s) {
;           kf[2 * s] = *(const bf16x8*)(ks + (sub * 64 + r32) * KR + (map * 64 + s * 16 + hh * 8) * 2);
;           kf[2 * s + 1] = *(const bf16x8*)(ks + (sub * 64 + 32 + r32) * KR + (map * 64 + s * 16 + hh * 8) * 2);
;         }
;         __builtin_amdgcn_sched_barrier(0); __builtin_amdgcn_s_setprio(1);
; #pragma unroll
;         for (int s = 0; s < 4; ++s) { s0 = mfma32(kf[2 * s], qf[s], s0); s1 = mfma32(kf[2 * s + 1], qf[s], s1); }
;       __builtin_amdgcn_s_setprio(0);
; }
;       if (relmin < 128 && relmax > -128) {
;         const int base = kbase - qpos + 255 + 4 * hh;
; #pragma unroll
;         for (int i = 0; i < 16; ++i) {
;           int i0 = base + (i & 3) + 8 * (i >> 2);
;           int i1 = i0 + 32;
;           i0 = i0 < 0 ? 0 : (i0 > 510 ? 510 : i0);
;           i1 = i1 < 0 ? 0 : (i1 > 510 ? 510 : i1);
;           s0[i] += tab[i0]; s1[i] += tab[i1];
;         }
;       }
.LBB0_568:
	v_add3_u32 v174, s45, v167, v165
	ds_read_b128 v[176:179], v174
	ds_read_b128 v[224:227], v174 offset:32
	ds_read_b128 v[228:231], v174 offset:8704
	ds_read_b128 v[232:235], v174 offset:8736
	ds_read_b128 v[242:245], v174 offset:64
	ds_read_b128 v[212:215], v174 offset:96
	ds_read_b128 v[216:219], v174 offset:8768
	ds_read_b128 v[220:223], v174 offset:8800
	s_add_i32 s44, s42, s24
	s_cmp_ge_i32 s44, 0xff
	s_cselect_b64 vcc, -1, 0
	s_cmp_le_i32 s44, 0xffffff41
	s_cselect_b64 s[2:3], -1, 0
	v_cndmask_b32_e64 v196, 0, v156, s[2:3]
	v_cndmask_b32_e32 v196, v196, v157, vcc
	v_sub_f32_e32 v196, v196, v169
	v_mov_b32_e32 v197, v196
	v_mov_b64_e32 v[198:199], v[196:197]
	v_mov_b64_e32 v[200:201], v[196:197]
	v_mov_b64_e32 v[202:203], v[196:197]
	v_mov_b64_e32 v[204:205], v[196:197]
	v_mov_b64_e32 v[206:207], v[196:197]
	v_mov_b64_e32 v[208:209], v[196:197]
	v_mov_b64_e32 v[210:211], v[196:197]
	s_nop 0
	s_waitcnt lgkmcnt(4)
	s_setprio 1
	v_mfma_f32_32x32x16_bf16 v[80:95], v[176:179], v[96:99], v[196:211]
	v_mfma_f32_32x32x16_bf16 v[64:79], v[228:231], v[96:99], v[196:211]
	v_mfma_f32_32x32x16_bf16 v[80:95], v[224:227], v[100:103], v[80:95]
	v_mfma_f32_32x32x16_bf16 v[64:79], v[232:235], v[100:103], v[64:79]
	s_waitcnt lgkmcnt(0)
	v_mfma_f32_32x32x16_bf16 v[80:95], v[242:245], v[104:107], v[80:95]
	v_mfma_f32_32x32x16_bf16 v[64:79], v[216:219], v[104:107], v[64:79]
	v_mfma_f32_32x32x16_bf16 v[80:95], v[212:215], v[108:111], v[80:95]
	v_mfma_f32_32x32x16_bf16 v[64:79], v[220:223], v[108:111], v[64:79]
	s_setprio 0
	s_or_b64 s[2:3], s[2:3], vcc
	v_add_u32_e32 v173, s24, v168
	s_and_b64 vcc, exec, s[2:3]
	s_cbranch_vccnz .LBB0_570
	v_add_u32_e32 v177, 0x100, v173
	s_add_i32 s2, 0, 0x25000
	v_med3_i32 v178, v177, 0, v192
	v_med3_i32 v177, v177, s33, v193
	v_lshl_add_u32 v180, v177, 2, s2
	v_add_u32_e32 v177, 0x101, v173
	v_lshl_add_u32 v179, v178, 2, s2
	v_med3_i32 v178, v177, 0, v192
	v_med3_i32 v177, v177, s33, v193
	v_add_u32_e32 v199, 0x108, v173
	v_add_u32_e32 v175, 0xff, v173
	v_lshl_add_u32 v196, v177, 2, s2
	v_add_u32_e32 v177, 0x102, v173
	v_med3_i32 v200, v199, 0, v192
	v_med3_i32 v199, v199, s33, v193
	v_med3_i32 v176, v175, 0, v192
	v_med3_i32 v175, v175, s33, v193
	v_lshl_add_u32 v181, v178, 2, s2
	v_med3_i32 v178, v177, 0, v192
	v_lshl_add_u32 v202, v199, 2, s2
	v_add_u32_e32 v199, 0x109, v173
	v_lshl_add_u32 v176, v176, 2, s2
	v_lshl_add_u32 v175, v175, 2, s2
	v_med3_i32 v177, v177, s33, v193
	v_lshl_add_u32 v197, v178, 2, s2
	v_lshl_add_u32 v201, v200, 2, s2
	v_med3_i32 v200, v199, 0, v192
	v_med3_i32 v199, v199, s33, v193
	v_add_u32_e32 v207, 0x110, v173
	v_lshl_add_u32 v198, v177, 2, s2
	ds_read_b32 v176, v176
	ds_read_b32 v178, v175 offset:128
	ds_read_b32 v177, v179
	ds_read_b32 v179, v180 offset:128
	ds_read_b32 v180, v181
	ds_read_b32 v196, v196 offset:128
	ds_read_b32 v181, v197
	ds_read_b32 v197, v198 offset:128
	v_add_u32_e32 v175, 0x107, v173
	v_lshl_add_u32 v204, v199, 2, s2
	v_add_u32_e32 v199, 0x10a, v173
	v_med3_i32 v208, v207, 0, v192
	v_med3_i32 v207, v207, s33, v193
	v_med3_i32 v198, v175, 0, v192
	v_med3_i32 v175, v175, s33, v193
	v_lshl_add_u32 v203, v200, 2, s2
	v_med3_i32 v200, v199, 0, v192
	v_lshl_add_u32 v210, v207, 2, s2
	v_add_u32_e32 v207, 0x111, v173
	v_lshl_add_u32 v198, v198, 2, s2
	v_lshl_add_u32 v175, v175, 2, s2
	v_med3_i32 v199, v199, s33, v193
	v_lshl_add_u32 v205, v200, 2, s2
	v_lshl_add_u32 v209, v208, 2, s2
	v_med3_i32 v208, v207, 0, v192
	v_med3_i32 v207, v207, s33, v193
	v_add_u32_e32 v215, 0x118, v173
	v_lshl_add_u32 v206, v199, 2, s2
	ds_read_b32 v198, v198
	ds_read_b32 v200, v175 offset:128
	ds_read_b32 v199, v201
	ds_read_b32 v201, v202 offset:128
	ds_read_b32 v202, v203
	ds_read_b32 v204, v204 offset:128
	ds_read_b32 v203, v205
	ds_read_b32 v205, v206 offset:128
	v_add_u32_e32 v175, 0x10f, v173
	v_lshl_add_u32 v212, v207, 2, s2
	v_add_u32_e32 v207, 0x112, v173
	v_med3_i32 v216, v215, 0, v192
	v_med3_i32 v215, v215, s33, v193
	v_med3_i32 v206, v175, 0, v192
	v_med3_i32 v175, v175, s33, v193
	v_lshl_add_u32 v211, v208, 2, s2
	v_med3_i32 v208, v207, 0, v192
	v_lshl_add_u32 v222, v215, 2, s2
	v_add_u32_e32 v215, 0x119, v173
	v_lshl_add_u32 v206, v206, 2, s2
	v_lshl_add_u32 v175, v175, 2, s2
	v_med3_i32 v207, v207, s33, v193
	v_lshl_add_u32 v213, v208, 2, s2
	v_lshl_add_u32 v217, v216, 2, s2
	v_med3_i32 v216, v215, 0, v192
	v_med3_i32 v215, v215, s33, v193
	v_lshl_add_u32 v214, v207, 2, s2
	ds_read_b32 v206, v206
	ds_read_b32 v208, v175 offset:128
	ds_read_b32 v207, v209
	ds_read_b32 v209, v210 offset:128
	ds_read_b32 v210, v211
	ds_read_b32 v212, v212 offset:128
	ds_read_b32 v211, v213
	ds_read_b32 v213, v214 offset:128
	v_add_u32_e32 v175, 0x117, v173
	v_lshl_add_u32 v220, v215, 2, s2
	v_add_u32_e32 v215, 0x11a, v173
	v_med3_i32 v214, v175, 0, v192
	v_lshl_add_u32 v218, v216, 2, s2
	v_med3_i32 v216, v215, 0, v192
	v_med3_i32 v215, v215, s33, v193
	v_med3_i32 v175, v175, s33, v193
	v_lshl_add_u32 v214, v214, 2, s2
	v_lshl_add_u32 v219, v216, 2, s2
	v_lshl_add_u32 v221, v215, 2, s2
	v_lshl_add_u32 v175, v175, 2, s2
	ds_read_b32 v214, v214
	ds_read_b32 v216, v175 offset:128
	ds_read_b32 v218, v218
	ds_read_b32 v219, v219
	ds_read_b32 v215, v217
	ds_read_b32 v221, v221 offset:128
	ds_read_b32 v220, v220 offset:128
	ds_read_b32 v217, v222 offset:128
	s_waitcnt lgkmcnt(4)
	v_pk_add_f32 v[94:95], v[94:95], v[218:219]
	s_waitcnt lgkmcnt(3)
	v_pk_add_f32 v[92:93], v[92:93], v[214:215]
	v_pk_add_f32 v[90:91], v[90:91], v[210:211]
	v_pk_add_f32 v[88:89], v[88:89], v[206:207]
	v_pk_add_f32 v[86:87], v[86:87], v[202:203]
	v_pk_add_f32 v[84:85], v[84:85], v[198:199]
	v_pk_add_f32 v[82:83], v[82:83], v[180:181]
	v_pk_add_f32 v[80:81], v[80:81], v[176:177]
	s_waitcnt lgkmcnt(1)
	v_pk_add_f32 v[78:79], v[78:79], v[220:221]
	s_waitcnt lgkmcnt(0)
	v_pk_add_f32 v[76:77], v[76:77], v[216:217]
	v_pk_add_f32 v[74:75], v[74:75], v[212:213]
	v_pk_add_f32 v[72:73], v[72:73], v[208:209]
	v_pk_add_f32 v[70:71], v[70:71], v[204:205]
	v_pk_add_f32 v[68:69], v[68:69], v[200:201]
	v_pk_add_f32 v[66:67], v[66:67], v[196:197]
	v_pk_add_f32 v[64:65], v[64:65], v[178:179]

; DI f32x16 mfma32(bf16x8 a, bf16x8 b, f32x16 c) { return __builtin_amdgcn_mfma_f32_32x32x16_bf16(a, b, c, 0, 0, 0); }
; DI void attn_diff_unit(const Params& p, int li, int b, int h, int qb, char* smem, bool pre, int nh, bool has_next) {
;     ...
;       {
;         bf16x8 kf[8];
; #pragma unroll
;         for (int s = 0; s < 4; ++s) {
;           kf[2 * s] = *(const bf16x8*)(ks + (sub * 64 + r32) * KR + (map * 64 + s * 16 + hh * 8) * 2);
;           kf[2 * s + 1] = *(const bf16x8*)(ks + (sub * 64 + 32 + r32) * KR + (map * 64 + s * 16 + hh * 8) * 2);
;         }
;         __builtin_amdgcn_sched_barrier(0); __builtin_amdgcn_s_setprio(1);
; #pragma unroll
;         for (int s = 0; s < 4; ++s) { s0 = mfma32(kf[2 * s], qf[s], s0); s1 = mfma32(kf[2 * s + 1], qf[s], s1); }
;       __builtin_amdgcn_s_setprio(0);
; }
;       if (relmin < 128 && relmax > -128) {
;         const int base = kbase - qpos + 255 + 4 * hh;
; #pragma unroll
;         for (int i = 0; i < 16; ++i) {
;           int i0 = base + (i & 3) + 8 * (i >> 2);
;           int i1 = i0 + 32;
;           i0 = i0 < 0 ? 0 : (i0 > 510 ? 510 : i0);
;           i1 = i1 < 0 ? 0 : (i1 > 510 ? 510 : i1);
;           s0[i] += tab[i0]; s1[i] += tab[i1];
;         }
;       }
.Ldp_i1_done:
	s_waitcnt lgkmcnt(0)
	s_nop 0
	s_setprio 1
	v_mfma_f32_32x32x16_bf16 v[80:95], v[212:215], v[96:99], v[196:211]
	v_mfma_f32_32x32x16_bf16 v[196:211], v[216:219], v[96:99], v[196:211]
	v_mfma_f32_32x32x16_bf16 v[80:95], v[220:223], v[100:103], v[80:95]
	v_mfma_f32_32x32x16_bf16 v[196:211], v[224:227], v[100:103], v[196:211]
	v_mfma_f32_32x32x16_bf16 v[80:95], v[228:231], v[104:107], v[80:95]
	v_mfma_f32_32x32x16_bf16 v[196:211], v[232:235], v[104:107], v[196:211]
	v_mfma_f32_32x32x16_bf16 v[80:95], v[176:179], v[108:111], v[80:95]
	v_mfma_f32_32x32x16_bf16 v[196:211], v[242:245], v[108:111], v[196:211]
	s_setprio 0
	s_or_b64 s[2:3], s[2:3], vcc
	s_and_b64 vcc, exec, s[2:3]
	s_cbranch_vccnz .Ldp_b1_skip
	s_add_i32 s2, 0, 0x25000
	v_add_u32_e32 v212, 0x13f, v173
	v_add_u32_e32 v228, 0x13f, v173
	v_add_u32_e32 v213, 0x140, v173
	v_add_u32_e32 v229, 0x140, v173
	v_add_u32_e32 v214, 0x141, v173
	v_add_u32_e32 v230, 0x141, v173
	v_add_u32_e32 v215, 0x142, v173
	v_add_u32_e32 v231, 0x142, v173
	v_add_u32_e32 v216, 0x147, v173
	v_add_u32_e32 v232, 0x147, v173
	v_add_u32_e32 v217, 0x148, v173
	v_add_u32_e32 v233, 0x148, v173
	v_add_u32_e32 v218, 0x149, v173
	v_add_u32_e32 v234, 0x149, v173
	v_add_u32_e32 v219, 0x14a, v173
	v_add_u32_e32 v235, 0x14a, v173
	v_add_u32_e32 v220, 0x14f, v173
	v_add_u32_e32 v176, 0x14f, v173
	v_add_u32_e32 v221, 0x150, v173
	v_add_u32_e32 v177, 0x150, v173
	v_add_u32_e32 v222, 0x151, v173
	v_add_u32_e32 v178, 0x151, v173
	v_add_u32_e32 v223, 0x152, v173
	v_add_u32_e32 v179, 0x152, v173
	v_add_u32_e32 v224, 0x157, v173
	v_add_u32_e32 v242, 0x157, v173
	v_add_u32_e32 v225, 0x158, v173
	v_add_u32_e32 v243, 0x158, v173
	v_add_u32_e32 v226, 0x159, v173
	v_add_u32_e32 v244, 0x159, v173
	v_add_u32_e32 v227, 0x15a, v173
	v_add_u32_e32 v245, 0x15a, v173
	v_med3_i32 v212, v212, 0, v192
	v_med3_i32 v228, v228, s33, v193
	v_med3_i32 v213, v213, 0, v192
	v_med3_i32 v229, v229, s33, v193
	v_med3_i32 v214, v214, 0, v192
	v_med3_i32 v230, v230, s33, v193
	v_med3_i32 v215, v215, 0, v192
	v_med3_i32 v231, v231, s33, v193
	v_med3_i32 v216, v216, 0, v192
	v_med3_i32 v232, v232, s33, v193
	v_med3_i32 v217, v217, 0, v192
	v_med3_i32 v233, v233, s33, v193
	v_med3_i32 v218, v218, 0, v192
	v_med3_i32 v234, v234, s33, v193
	v_med3_i32 v219, v219, 0, v192
	v_med3_i32 v235, v235, s33, v193
	v_med3_i32 v220, v220, 0, v192
	v_med3_i32 v176, v176, s33, v193
	v_med3_i32 v221, v221, 0, v192
	v_med3_i32 v177, v177, s33, v193
	v_med3_i32 v222, v222, 0, v192
	v_med3_i32 v178, v178, s33, v193
	v_med3_i32 v223, v223, 0, v192
	v_med3_i32 v179, v179, s33, v193
	v_med3_i32 v224, v224, 0, v192
	v_med3_i32 v242, v242, s33, v193
	v_med3_i32 v225, v225, 0, v192
	v_med3_i32 v243, v243, s33, v193
	v_med3_i32 v226, v226, 0, v192
	v_med3_i32 v244, v244, s33, v193
	v_med3_i32 v227, v227, 0, v192
	v_med3_i32 v245, v245, s33, v193
	v_lshl_add_u32 v212, v212, 2, s2
	v_lshl_add_u32 v228, v228, 2, s2
	v_lshl_add_u32 v213, v213, 2, s2
	v_lshl_add_u32 v229, v229, 2, s2
	v_lshl_add_u32 v214, v214, 2, s2
	v_lshl_add_u32 v230, v230, 2, s2
	v_lshl_add_u32 v215, v215, 2, s2
	v_lshl_add_u32 v231, v231, 2, s2
	v_lshl_add_u32 v216, v216, 2, s2
	v_lshl_add_u32 v232, v232, 2, s2
	v_lshl_add_u32 v217, v217, 2, s2
	v_lshl_add_u32 v233, v233, 2, s2
	v_lshl_add_u32 v218, v218, 2, s2
	v_lshl_add_u32 v234, v234, 2, s2
	v_lshl_add_u32 v219, v219, 2, s2
	v_lshl_add_u32 v235, v235, 2, s2
	v_lshl_add_u32 v220, v220, 2, s2
	v_lshl_add_u32 v176, v176, 2, s2
	v_lshl_add_u32 v221, v221, 2, s2
	v_lshl_add_u32 v177, v177, 2, s2
	v_lshl_add_u32 v222, v222, 2, s2
	v_lshl_add_u32 v178, v178, 2, s2
	v_lshl_add_u32 v223, v223, 2, s2
	v_lshl_add_u32 v179, v179, 2, s2
	v_lshl_add_u32 v224, v224, 2, s2
	v_lshl_add_u32 v242, v242, 2, s2
	v_lshl_add_u32 v225, v225, 2, s2
	v_lshl_add_u32 v243, v243, 2, s2
	v_lshl_add_u32 v226, v226, 2, s2
	v_lshl_add_u32 v244, v244, 2, s2
	v_lshl_add_u32 v227, v227, 2, s2
	v_lshl_add_u32 v245, v245, 2, s2
	ds_read_b32 v212, v212
	ds_read_b32 v228, v228 offset:128
	ds_read_b32 v213, v213
	ds_read_b32 v229, v229 offset:128
	ds_read_b32 v214, v214
	ds_read_b32 v230, v230 offset:128
	ds_read_b32 v215, v215
	ds_read_b32 v231, v231 offset:128
	ds_read_b32 v216, v216
	ds_read_b32 v232, v232 offset:128
	ds_read_b32 v217, v217
	ds_read_b32 v233, v233 offset:128
	ds_read_b32 v218, v218
	ds_read_b32 v234, v234 offset:128
	ds_read_b32 v219, v219
	ds_read_b32 v235, v235 offset:128
	ds_read_b32 v220, v220
	ds_read_b32 v176, v176 offset:128
	ds_read_b32 v221, v221
	ds_read_b32 v177, v177 offset:128
	ds_read_b32 v222, v222
	ds_read_b32 v178, v178 offset:128
	ds_read_b32 v223, v223
	ds_read_b32 v179, v179 offset:128
	ds_read_b32 v224, v224
	ds_read_b32 v242, v242 offset:128
	ds_read_b32 v225, v225
	ds_read_b32 v243, v243 offset:128
	ds_read_b32 v226, v226
	ds_read_b32 v244, v244 offset:128
	ds_read_b32 v227, v227
	ds_read_b32 v245, v245 offset:128
	s_waitcnt lgkmcnt(0)
	v_add_f32_e32 v80, v80, v212
	v_add_f32_e32 v196, v196, v228
	v_add_f32_e32 v81, v81, v213
	v_add_f32_e32 v197, v197, v229
	v_add_f32_e32 v82, v82, v214
	v_add_f32_e32 v198, v198, v230
	v_add_f32_e32 v83, v83, v215
	v_add_f32_e32 v199, v199, v231
	v_add_f32_e32 v84, v84, v216
	v_add_f32_e32 v200, v200, v232
	v_add_f32_e32 v85, v85, v217
	v_add_f32_e32 v201, v201, v233
	v_add_f32_e32 v86, v86, v218
	v_add_f32_e32 v202, v202, v234
	v_add_f32_e32 v87, v87, v219
	v_add_f32_e32 v203, v203, v235
	v_add_f32_e32 v88, v88, v220
	v_add_f32_e32 v204, v204, v176
	v_add_f32_e32 v89, v89, v221
	v_add_f32_e32 v205, v205, v177
	v_add_f32_e32 v90, v90, v222
	v_add_f32_e32 v206, v206, v178
	v_add_f32_e32 v91, v91, v223
	v_add_f32_e32 v207, v207, v179
	v_add_f32_e32 v92, v92, v224
	v_add_f32_e32 v208, v208, v242
	v_add_f32_e32 v93, v93, v225
	v_add_f32_e32 v209, v209, v243
	v_add_f32_e32 v94, v94, v226
	v_add_f32_e32 v210, v210, v244
	v_add_f32_e32 v95, v95, v227
	v_add_f32_e32 v211, v211, v245
; DI f32x16 mfma32(bf16x8 a, bf16x8 b, f32x16 c) { return __builtin_amdgcn_mfma_f32_32x32x16_bf16(a, b, c, 0, 0, 0); }
; DI bool softmax_tile(f32x16& s0, f32x16& s1, float& m, float& l, float& alpha, bf16x8* pf, int lane, bool first, bool check) {
;     ...
;   for (int i = 0; i < 16; ++i) { s0[i] = __builtin_amdgcn_exp2f(s0[i]); sum += s0[i]; }
; #pragma unroll
;   for (int i = 0; i < 16; ++i) { s1[i] = __builtin_amdgcn_exp2f(s1[i]); sum += s1[i]; }
;   l += sum;
;   pf[0] = pack8(s0, 0); pf[1] = pack8(s0, 8); pf[2] = pack8(s1, 0); pf[3] = pack8(s1, 8);
; DI void attn_diff_unit(const Params& p, int li, int b, int h, int qb, char* smem, bool pre, int nh, bool has_next) {
;     ...
;       float alpha; bf16x8 pf[4];
;       const bool resc = softmax_tile(s0, s1, m, l, alpha, pf, lane, (kt == 0) && (sub == 0), (sub == 0) && ((kt & 3) == 0));
;       {
;         bf16x8 vf[2][4];
; #pragma unroll
;         for (int j = 0; j < 4; ++j) vf[0][j] = ld_vfrag_tr(vs, vbase, VR, sub * 64, j * 32);
; #pragma unroll
;         for (int s = 0; s < 4; ++s) {
;           if (s < 3) {
; #pragma unroll
;             for (int j = 0; j < 4; ++j) vf[(s + 1) & 1][j] = ld_vfrag_tr(vs, vbase, VR, sub * 64 + 16 * (s + 1), j * 32);
;           }
;           __builtin_amdgcn_sched_barrier(0); __builtin_amdgcn_s_setprio(1);
; #pragma unroll
;           for (int j = 0; j < 4; ++j) O[j] = mfma32(vf[s & 1][j], pf[s], O[j]);
;         __builtin_amdgcn_s_setprio(0);
; }
.Ldp_b1_skip:
	ds_read_b64_tr_b16 v[212:213], v175 offset:34816
	ds_read_b64_tr_b16 v[214:215], v175 offset:37376
	ds_read_b64_tr_b16 v[216:217], v175 offset:34880
	ds_read_b64_tr_b16 v[218:219], v175 offset:37440
	ds_read_b64_tr_b16 v[220:221], v175 offset:34944
	ds_read_b64_tr_b16 v[222:223], v175 offset:37504
	ds_read_b64_tr_b16 v[224:225], v175 offset:35008
	ds_read_b64_tr_b16 v[226:227], v175 offset:37568
	ds_read_b64_tr_b16 v[228:229], v175 offset:39936
	ds_read_b64_tr_b16 v[230:231], v175 offset:42496
	ds_read_b64_tr_b16 v[232:233], v175 offset:40000
	ds_read_b64_tr_b16 v[234:235], v175 offset:42560
	ds_read_b64_tr_b16 v[176:177], v175 offset:40064
	ds_read_b64_tr_b16 v[178:179], v175 offset:42624
	ds_read_b64_tr_b16 v[242:243], v175 offset:40128
	ds_read_b64_tr_b16 v[244:245], v175 offset:42688
	s_waitcnt lgkmcnt(8)
	s_setprio 1
	v_mfma_f32_32x32x16_bf16 v[48:63], v[212:215], v[72:75], v[48:63]
	v_exp_f32_e32 v80, v80
	v_exp_f32_e32 v81, v81
	v_mfma_f32_32x32x16_bf16 v[32:47], v[216:219], v[72:75], v[32:47]
	v_exp_f32_e32 v82, v82
	v_exp_f32_e32 v83, v83
	v_add_f32_e32 v253, v81, v80
	v_mfma_f32_32x32x16_bf16 v[16:31], v[220:223], v[72:75], v[16:31]
	v_exp_f32_e32 v84, v84
	v_exp_f32_e32 v85, v85
	v_add_f32_e32 v253, v82, v253
	v_add_f32_e32 v253, v83, v253
	v_mfma_f32_32x32x16_bf16 v[0:15], v[224:227], v[72:75], v[0:15]
	v_exp_f32_e32 v86, v86
	v_exp_f32_e32 v87, v87
	v_add_f32_e32 v253, v84, v253
	v_add_f32_e32 v253, v85, v253
	ds_read_b64_tr_b16 v[212:213], v175 offset:45056
	ds_read_b64_tr_b16 v[214:215], v175 offset:47616
	ds_read_b64_tr_b16 v[216:217], v175 offset:45120
	ds_read_b64_tr_b16 v[218:219], v175 offset:47680
	ds_read_b64_tr_b16 v[220:221], v175 offset:45184
	ds_read_b64_tr_b16 v[222:223], v175 offset:47744
	ds_read_b64_tr_b16 v[224:225], v175 offset:45248
	ds_read_b64_tr_b16 v[226:227], v175 offset:47808
	s_waitcnt lgkmcnt(8)
	v_mfma_f32_32x32x16_bf16 v[48:63], v[228:231], v[76:79], v[48:63]
	v_exp_f32_e32 v88, v88
	v_exp_f32_e32 v89, v89
	v_add_f32_e32 v253, v86, v253
	v_add_f32_e32 v253, v87, v253
	v_cvt_pk_bf16_f32 v80, v80, v81
	v_mfma_f32_32x32x16_bf16 v[32:47], v[232:235], v[76:79], v[32:47]
	v_exp_f32_e32 v90, v90
	v_exp_f32_e32 v91, v91
	v_add_f32_e32 v253, v88, v253
	v_add_f32_e32 v253, v89, v253
	v_cvt_pk_bf16_f32 v81, v82, v83
	v_mfma_f32_32x32x16_bf16 v[16:31], v[176:179], v[76:79], v[16:31]
	v_exp_f32_e32 v92, v92
	v_exp_f32_e32 v93, v93
	v_add_f32_e32 v253, v90, v253
	v_add_f32_e32 v253, v91, v253
	v_cvt_pk_bf16_f32 v82, v84, v85
	v_mfma_f32_32x32x16_bf16 v[0:15], v[242:245], v[76:79], v[0:15]
	v_exp_f32_e32 v94, v94
	v_exp_f32_e32 v95, v95
	v_add_f32_e32 v253, v92, v253
	v_add_f32_e32 v253, v93, v253
	v_cvt_pk_bf16_f32 v83, v86, v87
	ds_read_b64_tr_b16 v[228:229], v175 offset:50176
	ds_read_b64_tr_b16 v[230:231], v175 offset:52736
	ds_read_b64_tr_b16 v[232:233], v175 offset:50240
	ds_read_b64_tr_b16 v[234:235], v175 offset:52800
	ds_read_b64_tr_b16 v[176:177], v175 offset:50304
	ds_read_b64_tr_b16 v[178:179], v175 offset:52864
	ds_read_b64_tr_b16 v[242:243], v175 offset:50368
	ds_read_b64_tr_b16 v[244:245], v175 offset:52928
	s_waitcnt lgkmcnt(8)
	v_mfma_f32_32x32x16_bf16 v[48:63], v[212:215], v[64:67], v[48:63]
	v_exp_f32_e32 v196, v196
	v_exp_f32_e32 v197, v197
	v_add_f32_e32 v253, v94, v253
	v_add_f32_e32 v253, v95, v253
	v_cvt_pk_bf16_f32 v84, v88, v89
	v_mfma_f32_32x32x16_bf16 v[32:47], v[216:219], v[64:67], v[32:47]
	v_exp_f32_e32 v198, v198
	v_exp_f32_e32 v199, v199
	v_add_f32_e32 v253, v196, v253
	v_add_f32_e32 v253, v197, v253
	v_cvt_pk_bf16_f32 v85, v90, v91
	v_mfma_f32_32x32x16_bf16 v[16:31], v[220:223], v[64:67], v[16:31]
	v_exp_f32_e32 v200, v200
	v_exp_f32_e32 v201, v201
	v_add_f32_e32 v253, v198, v253
	v_add_f32_e32 v253, v199, v253
	v_cvt_pk_bf16_f32 v86, v92, v93
	v_mfma_f32_32x32x16_bf16 v[0:15], v[224:227], v[64:67], v[0:15]
	v_exp_f32_e32 v202, v202
	v_exp_f32_e32 v203, v203
	v_add_f32_e32 v253, v200, v253
	v_add_f32_e32 v253, v201, v253
	v_cvt_pk_bf16_f32 v87, v94, v95
	s_waitcnt lgkmcnt(0)
	v_mfma_f32_32x32x16_bf16 v[48:63], v[228:231], v[68:71], v[48:63]
	v_exp_f32_e32 v204, v204
	v_exp_f32_e32 v205, v205
	v_add_f32_e32 v253, v202, v253
	v_add_f32_e32 v253, v203, v253
	v_cvt_pk_bf16_f32 v196, v196, v197
	v_mfma_f32_32x32x16_bf16 v[32:47], v[232:235], v[68:71], v[32:47]
	v_exp_f32_e32 v206, v206
	v_exp_f32_e32 v207, v207
	v_add_f32_e32 v253, v204, v253
	v_add_f32_e32 v253, v205, v253
	v_cvt_pk_bf16_f32 v197, v198, v199
	v_mfma_f32_32x32x16_bf16 v[16:31], v[176:179], v[68:71], v[16:31]
	v_exp_f32_e32 v208, v208
	v_exp_f32_e32 v209, v209
	v_add_f32_e32 v253, v206, v253
	v_add_f32_e32 v253, v207, v253
	v_cvt_pk_bf16_f32 v198, v200, v201
	v_mfma_f32_32x32x16_bf16 v[0:15], v[242:245], v[68:71], v[0:15]
	s_setprio 0
	v_exp_f32_e32 v210, v210
	v_exp_f32_e32 v211, v211
	v_add_f32_e32 v253, v208, v253
	v_add_f32_e32 v253, v209, v253
	v_cvt_pk_bf16_f32 v199, v202, v203
	v_add_f32_e32 v253, v210, v253
	v_add_f32_e32 v253, v211, v253
	v_cvt_pk_bf16_f32 v200, v204, v205
	v_cvt_pk_bf16_f32 v201, v206, v207
	v_cvt_pk_bf16_f32 v202, v208, v209
	v_cvt_pk_bf16_f32 v203, v210, v211
	v_add_f32_e32 v172, v172, v253
	s_andn2_b64 vcc, exec, s[100:101]
	s_cbranch_vccnz .Ldp_nors
; DI f32x16 mfma32(bf16x8 a, bf16x8 b, f32x16 c) { return __builtin_amdgcn_mfma_f32_32x32x16_bf16(a, b, c, 0, 0, 0); }
; DI void attn_diff_unit(const Params& p, int li, int b, int h, int qb, char* smem, bool pre, int nh, bool has_next) {
;     ...
;         for (int s = 0; s < 4; ++s) {
;           if (s < 3) {
; #pragma unroll
;             for (int j = 0; j < 4; ++j) vf[(s + 1) & 1][j] = ld_vfrag_tr(vs, vbase, VR, sub * 64 + 16 * (s + 1), j * 32);
;           }
;           __builtin_amdgcn_sched_barrier(0); __builtin_amdgcn_s_setprio(1);
; #pragma unroll
;           for (int j = 0; j < 4; ++j) O[j] = mfma32(vf[s & 1][j], pf[s], O[j]);
;         __builtin_amdgcn_s_setprio(0);
; }
;       }
;       if (resc) {
; #pragma unroll
;         for (int j = 0; j < 4; ++j) scale16(O[j], alpha);
;       }
;     }
;     if (kt + 1 < 32) put_stage(smem + ((kt + 1) & 1) * STG);
;     else if (has_next) put_stage(smem);
	s_nop 15
	v_mul_f32_e32 v0, v0, v252
	v_mul_f32_e32 v1, v1, v252
	v_mul_f32_e32 v2, v2, v252
	v_mul_f32_e32 v3, v3, v252
	v_mul_f32_e32 v4, v4, v252
	v_mul_f32_e32 v5, v5, v252
	v_mul_f32_e32 v6, v6, v252
	v_mul_f32_e32 v7, v7, v252
	v_mul_f32_e32 v8, v8, v252
	v_mul_f32_e32 v9, v9, v252
	v_mul_f32_e32 v10, v10, v252
	v_mul_f32_e32 v11, v11, v252
	v_mul_f32_e32 v12, v12, v252
	v_mul_f32_e32 v13, v13, v252
	v_mul_f32_e32 v14, v14, v252
	v_mul_f32_e32 v15, v15, v252
	v_mul_f32_e32 v16, v16, v252
	v_mul_f32_e32 v17, v17, v252
	v_mul_f32_e32 v18, v18, v252
	v_mul_f32_e32 v19, v19, v252
	v_mul_f32_e32 v20, v20, v252
	v_mul_f32_e32 v21, v21, v252
	v_mul_f32_e32 v22, v22, v252
	v_mul_f32_e32 v23, v23, v252
	v_mul_f32_e32 v24, v24, v252
	v_mul_f32_e32 v25, v25, v252
	v_mul_f32_e32 v26, v26, v252
	v_mul_f32_e32 v27, v27, v252
	v_mul_f32_e32 v28, v28, v252
	v_mul_f32_e32 v29, v29, v252
	v_mul_f32_e32 v30, v30, v252
	v_mul_f32_e32 v31, v31, v252
	v_mul_f32_e32 v32, v32, v252
	v_mul_f32_e32 v33, v33, v252
	v_mul_f32_e32 v34, v34, v252
	v_mul_f32_e32 v35, v35, v252
	v_mul_f32_e32 v36, v36, v252
	v_mul_f32_e32 v37, v37, v252
	v_mul_f32_e32 v38, v38, v252
	v_mul_f32_e32 v39, v39, v252
	v_mul_f32_e32 v40, v40, v252
	v_mul_f32_e32 v41, v41, v252
	v_mul_f32_e32 v42, v42, v252
	v_mul_f32_e32 v43, v43, v252
	v_mul_f32_e32 v44, v44, v252
	v_mul_f32_e32 v45, v45, v252
	v_mul_f32_e32 v46, v46, v252
	v_mul_f32_e32 v47, v47, v252
	v_mul_f32_e32 v48, v48, v252
	v_mul_f32_e32 v49, v49, v252
	v_mul_f32_e32 v50, v50, v252
	v_mul_f32_e32 v51, v51, v252
	v_mul_f32_e32 v52, v52, v252
	v_mul_f32_e32 v53, v53, v252
	v_mul_f32_e32 v54, v54, v252
	v_mul_f32_e32 v55, v55, v252
	v_mul_f32_e32 v56, v56, v252
	v_mul_f32_e32 v57, v57, v252
	v_mul_f32_e32 v58, v58, v252
	v_mul_f32_e32 v59, v59, v252
	v_mul_f32_e32 v60, v60, v252
	v_mul_f32_e32 v61, v61, v252
	v_mul_f32_e32 v62, v62, v252
	v_mul_f32_e32 v63, v63, v252
.Ldp_nors:
	ds_read_b64_tr_b16 v[212:213], v175 offset:55296
	ds_read_b64_tr_b16 v[214:215], v175 offset:57856
	ds_read_b64_tr_b16 v[216:217], v175 offset:55360
	ds_read_b64_tr_b16 v[218:219], v175 offset:57920
	ds_read_b64_tr_b16 v[220:221], v175 offset:55424
	ds_read_b64_tr_b16 v[222:223], v175 offset:57984
	ds_read_b64_tr_b16 v[224:225], v175 offset:55488
	ds_read_b64_tr_b16 v[226:227], v175 offset:58048
	ds_read_b64_tr_b16 v[228:229], v175 offset:60416
	ds_read_b64_tr_b16 v[230:231], v175 offset:62976
	ds_read_b64_tr_b16 v[232:233], v175 offset:60480
	ds_read_b64_tr_b16 v[234:235], v175 offset:63040
	ds_read_b64_tr_b16 v[176:177], v175 offset:60544
	ds_read_b64_tr_b16 v[178:179], v175 offset:63104
	ds_read_b64_tr_b16 v[242:243], v175 offset:60608
	ds_read_b64_tr_b16 v[244:245], v175 offset:63168
	s_waitcnt lgkmcnt(8)
	s_setprio 1
	v_mfma_f32_32x32x16_bf16 v[48:63], v[212:215], v[80:83], v[48:63]
	v_mfma_f32_32x32x16_bf16 v[32:47], v[216:219], v[80:83], v[32:47]
	v_mfma_f32_32x32x16_bf16 v[16:31], v[220:223], v[80:83], v[16:31]
	v_mfma_f32_32x32x16_bf16 v[0:15], v[224:227], v[80:83], v[0:15]
	ds_read_b64_tr_b16 v[212:213], v236 offset:30720
	ds_read_b64_tr_b16 v[214:215], v236 offset:33280
	ds_read_b64_tr_b16 v[216:217], v236 offset:30784
	ds_read_b64_tr_b16 v[218:219], v236 offset:33344
	ds_read_b64_tr_b16 v[220:221], v236 offset:30848
	ds_read_b64_tr_b16 v[222:223], v236 offset:33408
	ds_read_b64_tr_b16 v[224:225], v236 offset:30912
	ds_read_b64_tr_b16 v[226:227], v236 offset:33472
	s_waitcnt lgkmcnt(8)
	v_mfma_f32_32x32x16_bf16 v[48:63], v[228:231], v[84:87], v[48:63]
	v_mfma_f32_32x32x16_bf16 v[32:47], v[232:235], v[84:87], v[32:47]
	v_mfma_f32_32x32x16_bf16 v[16:31], v[176:179], v[84:87], v[16:31]
	v_mfma_f32_32x32x16_bf16 v[0:15], v[242:245], v[84:87], v[0:15]
	ds_read_b64_tr_b16 v[228:229], v236 offset:35840
	ds_read_b64_tr_b16 v[230:231], v236 offset:38400
	ds_read_b64_tr_b16 v[232:233], v236 offset:35904
	ds_read_b64_tr_b16 v[234:235], v236 offset:38464
	ds_read_b64_tr_b16 v[176:177], v236 offset:35968
	ds_read_b64_tr_b16 v[178:179], v236 offset:38528
	ds_read_b64_tr_b16 v[242:243], v236 offset:36032
	ds_read_b64_tr_b16 v[244:245], v236 offset:38592
	s_waitcnt lgkmcnt(8)
	v_mfma_f32_32x32x16_bf16 v[48:63], v[212:215], v[196:199], v[48:63]
	v_mfma_f32_32x32x16_bf16 v[32:47], v[216:219], v[196:199], v[32:47]
	v_mfma_f32_32x32x16_bf16 v[16:31], v[220:223], v[196:199], v[16:31]
	v_mfma_f32_32x32x16_bf16 v[0:15], v[224:227], v[196:199], v[0:15]
	s_waitcnt lgkmcnt(0)
	v_mfma_f32_32x32x16_bf16 v[48:63], v[228:231], v[200:203], v[48:63]
	v_mfma_f32_32x32x16_bf16 v[32:47], v[232:235], v[200:203], v[32:47]
	v_mfma_f32_32x32x16_bf16 v[16:31], v[176:179], v[200:203], v[16:31]
	v_mfma_f32_32x32x16_bf16 v[0:15], v[242:245], v[200:203], v[0:15]
	s_setprio 0
	s_add_i32 s44, s43, 1
	s_cmpk_eq_i32 s24, 0xf80
	s_mov_b64 s[2:3], -1
	s_cbranch_scc1 .LBB0_583
	s_xor_b32 s2, s45, 0x12800
	v_add3_u32 v64, s2, v161, v159
	v_add3_u32 v65, s2, v160, v159
	s_mov_b64 s[2:3], 0
	s_waitcnt vmcnt(3)
	ds_write_b128 v64, v[116:119]
	v_add_u32_e32 v66, 0x8800, v65
	s_waitcnt vmcnt(1)
	ds_write_b128 v65, v[128:131] offset:34816
	s_waitcnt vmcnt(5)
	ds_write_b128 v64, v[112:115] offset:8704
	s_waitcnt vmcnt(4)
	ds_write_b128 v65, v[120:123] offset:45056
	s_waitcnt vmcnt(3)
	ds_write_b128 v64, v[124:127] offset:17408
	s_waitcnt vmcnt(2)
	ds_write_b128 v65, v[132:135] offset:55296
	s_waitcnt vmcnt(1)
	ds_write_b128 v64, v[136:139] offset:26112
	s_waitcnt vmcnt(0)
	ds_write_b128 v66, v[140:143] offset:30720
